# buffer_inv sc1 issued at barrier arrival (before the arrive atomic) instead of after release, 11 seam sites
# speedup vs baseline: 1.0086x; 1.0086x over previous
.LBB0_180:
.LBB0_181:
	s_waitcnt vmcnt(0)
	s_lshl_b32 s0, s44, 6
	s_mov_b32 s1, 0
	s_barrier
	s_mov_b64 s[2:3], exec
	v_readlane_b32 s4, v245, 3
	v_readlane_b32 s5, v245, 4
	s_and_b64 s[4:5], s[2:3], s[4:5]
	s_mov_b64 exec, s[4:5]
	s_cbranch_execz .LBB0_233
	s_add_u32 s4, s70, 0x200
	s_addc_u32 s5, s71, 0
	s_add_i32 s6, 0, 0x20160
	v_mov_b32_e32 v1, s6
	s_waitcnt vmcnt(0) expcnt(0) lgkmcnt(0)
	buffer_inv sc1
	ds_read_b32 v3, v1
	s_add_i32 s6, 0, 0x20164
	v_mov_b32_e32 v1, s6
	ds_read_b32 v1, v1
	s_waitcnt lgkmcnt(1)
	v_cmp_ne_u32_e32 vcc, 0, v3
	s_cbranch_vccnz .LBB0_197
	v_readlane_b32 s10, v245, 0
	s_add_u32 s6, s70, 0x1000
	v_readlane_b32 s11, v245, 1
	s_addc_u32 s7, s71, 0
	s_load_dwordx2 s[14:15], s[10:11], 0x4
	s_add_u32 s8, s70, 0x1100
	s_addc_u32 s9, s71, 0
	s_add_u32 s10, s70, 0x1200
	s_addc_u32 s11, s71, 0
	s_add_u32 s12, s70, 0x1300
	s_waitcnt lgkmcnt(0)
	s_mul_i32 s20, s14, s80
	s_addc_u32 s13, s71, 0
	s_mul_i32 s20, s20, s15
	s_mov_b32 s21, 1
	v_mov_b32_e32 v17, 0
	s_branch .LBB0_185

.LBB0_212:
	s_or_b64 exec, exec, s[10:11]
	s_waitcnt vmcnt(0)
	s_waitcnt vmcnt(0)

.LBB0_230:
	s_or_b64 exec, exec, s[4:5]
	s_mov_b64 s[4:5], exec
	v_mbcnt_lo_u32_b32 v1, s4, 0
	v_mbcnt_hi_u32_b32 v1, s5, v1
	v_cmp_eq_u32_e32 vcc, 0, v1
	s_waitcnt vmcnt(0)
	s_and_saveexec_b64 s[8:9], vcc
	s_cbranch_execz .LBB0_232
	s_bcnt1_i32_b64 s4, s[4:5]
	v_mov_b32_e32 v1, 0
	v_mov_b32_e32 v2, s4
	global_atomic_add v1, v2, s[6:7]

.LBB0_361:
	v_readlane_b32 s0, v238, 13
	s_add_i32 s38, s0, 2
	v_readlane_b32 s0, v245, 5
	v_readlane_b32 s1, v245, 6
	s_cmp_ge_i32 s38, s1
	s_cbranch_scc1 .LBB0_415
	s_waitcnt vmcnt(0)
	s_barrier
	s_mov_b64 s[0:1], exec
	v_readlane_b32 s10, v245, 3
	v_readlane_b32 s11, v245, 4
	s_and_b64 s[10:11], s[0:1], s[10:11]
	s_mov_b64 exec, s[10:11]
	s_cbranch_execz .LBB0_414
	v_readlane_b32 s10, v239, 5
	s_waitcnt vmcnt(0) expcnt(0) lgkmcnt(0)
	buffer_inv sc1
	s_nop 0
	v_mov_b32_e32 v2, s10
	ds_read_b32 v4, v2
	v_readlane_b32 s10, v239, 6
	s_waitcnt lgkmcnt(0)
	v_cmp_ne_u32_e32 vcc, 0, v4
	v_mov_b32_e32 v2, s10
	ds_read_b32 v2, v2
	s_cbranch_vccnz .LBB0_378
	v_readlane_b32 s14, v245, 0
	v_readlane_b32 s15, v245, 1
	s_load_dwordx2 s[10:11], s[14:15], 0x4
	s_mov_b32 s21, 1
	s_waitcnt lgkmcnt(0)
	s_mul_i32 s20, s10, s80
	s_mul_i32 s20, s20, s11
	s_branch .LBB0_366

.LBB0_393:
	s_or_b64 exec, exec, s[14:15]
	s_waitcnt vmcnt(0)
	s_waitcnt vmcnt(0)

.LBB0_411:
	s_or_b64 exec, exec, s[10:11]
	s_mov_b64 s[10:11], exec
	v_mbcnt_lo_u32_b32 v2, s10, 0
	v_mbcnt_hi_u32_b32 v2, s11, v2
	v_cmp_eq_u32_e32 vcc, 0, v2
	s_waitcnt vmcnt(0)
	s_and_saveexec_b64 s[14:15], vcc
	s_cbranch_execz .LBB0_413
	s_bcnt1_i32_b64 s10, s[10:11]
	v_mov_b32_e32 v2, s10
	v_readlane_b32 s10, v245, 61
	v_readlane_b32 s11, v245, 62
	s_nop 4
	global_atomic_add v173, v2, s[10:11]

.LBB0_564:
	v_readlane_b32 s0, v238, 13
	s_add_i32 s38, s0, 3
	v_readlane_b32 s0, v245, 5
	v_readlane_b32 s1, v245, 6
	s_cmp_lt_i32 s38, s1
	s_cbranch_scc0 .LBB0_576
	s_waitcnt vmcnt(0)
	s_barrier
	s_mov_b64 s[0:1], exec
	v_readlane_b32 s10, v245, 3
	v_readlane_b32 s11, v245, 4
	v_readlane_b32 s70, v239, 62
	v_readlane_b32 s54, v238, 3
	v_readlane_b32 s56, v238, 5
	s_and_b64 s[10:11], s[0:1], s[10:11]
	v_readlane_b32 s71, v239, 63
	v_readlane_b32 s55, v238, 4
	v_readlane_b32 s57, v238, 6
	s_mov_b64 exec, s[10:11]
	s_cbranch_execz .LBB0_618
	v_readlane_b32 s10, v239, 5
	s_waitcnt vmcnt(0) expcnt(0) lgkmcnt(0)
	buffer_inv sc1
	s_nop 0
	v_mov_b32_e32 v2, s10
	ds_read_b32 v4, v2
	v_readlane_b32 s10, v239, 6
	s_waitcnt lgkmcnt(0)
	v_cmp_ne_u32_e32 vcc, 0, v4
	v_mov_b32_e32 v2, s10
	ds_read_b32 v2, v2
	s_cbranch_vccnz .LBB0_582
	v_readlane_b32 s14, v245, 0
	v_readlane_b32 s15, v245, 1
	s_load_dwordx2 s[10:11], s[14:15], 0x4
	s_mov_b32 s21, 1
	s_waitcnt lgkmcnt(0)
	s_mul_i32 s20, s10, s80
	s_mul_i32 s20, s20, s11
	s_branch .LBB0_569

.LBB0_649:
	v_readlane_b32 s0, v238, 13
	s_add_i32 s38, s0, 4
	v_readlane_b32 s0, v245, 5
	v_readlane_b32 s1, v245, 6
	s_cmp_ge_i32 s38, s1
	s_cbranch_scc1 .LBB0_703
	s_waitcnt vmcnt(0)
	s_barrier
	s_mov_b64 s[0:1], exec
	v_readlane_b32 s10, v245, 3
	v_readlane_b32 s11, v245, 4
	s_and_b64 s[10:11], s[0:1], s[10:11]
	s_mov_b64 exec, s[10:11]
	s_cbranch_execz .LBB0_702
	v_readlane_b32 s10, v239, 5
	s_waitcnt vmcnt(0) expcnt(0) lgkmcnt(0)
	buffer_inv sc1
	s_nop 0
	v_mov_b32_e32 v2, s10
	ds_read_b32 v4, v2
	v_readlane_b32 s10, v239, 6
	s_waitcnt lgkmcnt(0)
	v_cmp_ne_u32_e32 vcc, 0, v4
	v_mov_b32_e32 v2, s10
	ds_read_b32 v2, v2
	s_cbranch_vccnz .LBB0_666
	v_readlane_b32 s14, v245, 0
	v_readlane_b32 s15, v245, 1
	s_load_dwordx2 s[10:11], s[14:15], 0x4
	s_mov_b32 s21, 1
	s_waitcnt lgkmcnt(0)
	s_mul_i32 s20, s10, s80
	s_mul_i32 s20, s20, s11
	s_branch .LBB0_654

.LBB0_832:
	v_readlane_b32 s0, v238, 13
	s_add_i32 s38, s0, 5
	v_readlane_b32 s0, v245, 5
	v_readlane_b32 s1, v245, 6
	s_cmp_ge_i32 s38, s1
	s_barrier
	s_cbranch_scc1 .LBB0_886
	s_waitcnt vmcnt(0)
	s_barrier
	s_mov_b64 s[0:1], exec
	v_readlane_b32 s10, v245, 3
	v_readlane_b32 s11, v245, 4
	s_and_b64 s[10:11], s[0:1], s[10:11]
	s_mov_b64 exec, s[10:11]
	s_cbranch_execz .LBB0_885
	v_readlane_b32 s10, v239, 5
	s_waitcnt vmcnt(0) expcnt(0) lgkmcnt(0)
	buffer_inv sc1
	s_nop 0
	v_mov_b32_e32 v2, s10
	ds_read_b32 v4, v2
	v_readlane_b32 s10, v239, 6
	s_waitcnt lgkmcnt(0)
	v_cmp_ne_u32_e32 vcc, 0, v4
	v_mov_b32_e32 v2, s10
	ds_read_b32 v2, v2
	s_cbranch_vccnz .LBB0_849
	v_readlane_b32 s14, v245, 0
	v_readlane_b32 s15, v245, 1
	s_load_dwordx2 s[10:11], s[14:15], 0x4
	s_mov_b32 s21, 1
	s_waitcnt lgkmcnt(0)
	s_mul_i32 s20, s10, s80
	s_mul_i32 s20, s20, s11
	s_branch .LBB0_837

.LBB0_942:
	v_readlane_b32 s0, v238, 13
	s_add_i32 s38, s0, 6
	v_readlane_b32 s0, v245, 5
	v_readlane_b32 s1, v245, 6
	s_cmp_ge_i32 s38, s1
	s_cbranch_scc1 .LBB0_996
	s_waitcnt vmcnt(0)
	s_waitcnt vmcnt(0) lgkmcnt(0)
	s_barrier
	s_mov_b64 s[0:1], exec
	v_readlane_b32 s10, v245, 3
	v_readlane_b32 s11, v245, 4
	s_and_b64 s[10:11], s[0:1], s[10:11]
	s_mov_b64 exec, s[10:11]
	s_cbranch_execz .LBB0_995
	v_readlane_b32 s10, v239, 5
	s_waitcnt vmcnt(0) expcnt(0) lgkmcnt(0)
	buffer_inv sc1
	s_nop 0
	v_mov_b32_e32 v2, s10
	ds_read_b32 v4, v2
	v_readlane_b32 s10, v239, 6
	s_waitcnt lgkmcnt(0)
	v_cmp_ne_u32_e32 vcc, 0, v4
	v_mov_b32_e32 v2, s10
	ds_read_b32 v2, v2
	s_cbranch_vccnz .LBB0_959
	v_readlane_b32 s14, v245, 0
	v_readlane_b32 s15, v245, 1
	s_load_dwordx2 s[10:11], s[14:15], 0x4
	s_mov_b32 s21, 1
	s_waitcnt lgkmcnt(0)
	s_mul_i32 s20, s10, s80
	s_mul_i32 s20, s20, s11
	s_branch .LBB0_947

.LBB0_1032:
	v_readlane_b32 s0, v238, 13
	s_add_i32 s38, s0, 7
	v_readlane_b32 s0, v245, 5
	v_readlane_b32 s1, v245, 6
	s_cmp_ge_i32 s38, s1
	s_cbranch_scc1 .LBB0_1086
	s_waitcnt vmcnt(0)
	s_waitcnt vmcnt(0) lgkmcnt(0)
	s_barrier
	s_mov_b64 s[0:1], exec
	v_readlane_b32 s10, v245, 3
	v_readlane_b32 s11, v245, 4
	s_and_b64 s[10:11], s[0:1], s[10:11]
	s_mov_b64 exec, s[10:11]
	s_cbranch_execz .LBB0_1085
	v_readlane_b32 s10, v239, 5
	s_waitcnt vmcnt(0) expcnt(0) lgkmcnt(0)
	buffer_inv sc1
	s_nop 0
	v_mov_b32_e32 v2, s10
	ds_read_b32 v4, v2
	v_readlane_b32 s10, v239, 6
	s_waitcnt lgkmcnt(0)
	v_cmp_ne_u32_e32 vcc, 0, v4
	v_mov_b32_e32 v2, s10
	ds_read_b32 v2, v2
	s_cbranch_vccnz .LBB0_1049
	v_readlane_b32 s14, v245, 0
	v_readlane_b32 s15, v245, 1
	s_load_dwordx2 s[10:11], s[14:15], 0x4
	s_mov_b32 s21, 1
	s_waitcnt lgkmcnt(0)
	s_mul_i32 s20, s10, s80
	s_mul_i32 s20, s20, s11
	s_branch .LBB0_1037

.LBB0_1099:
	v_readlane_b32 s0, v238, 13
	s_add_i32 s38, s0, 8
	v_readlane_b32 s0, v245, 5
	v_readlane_b32 s1, v245, 6
	s_cmp_ge_i32 s38, s1
	s_cbranch_scc1 .LBB0_1153
	s_waitcnt vmcnt(0)
	s_waitcnt vmcnt(0) lgkmcnt(0)
	s_barrier
	s_mov_b64 s[0:1], exec
	v_readlane_b32 s10, v245, 3
	v_readlane_b32 s11, v245, 4
	s_and_b64 s[10:11], s[0:1], s[10:11]
	s_mov_b64 exec, s[10:11]
	s_cbranch_execz .LBB0_1152
	v_readlane_b32 s10, v239, 5
	s_waitcnt vmcnt(0) expcnt(0) lgkmcnt(0)
	buffer_inv sc1
	s_nop 0
	v_mov_b32_e32 v2, s10
	ds_read_b32 v4, v2
	v_readlane_b32 s10, v239, 6
	s_waitcnt lgkmcnt(0)
	v_cmp_ne_u32_e32 vcc, 0, v4
	v_mov_b32_e32 v2, s10
	ds_read_b32 v2, v2
	s_cbranch_vccnz .LBB0_1116
	v_readlane_b32 s14, v245, 0
	v_readlane_b32 s15, v245, 1
	s_load_dwordx2 s[10:11], s[14:15], 0x4
	s_mov_b32 s21, 1
	s_waitcnt lgkmcnt(0)
	s_mul_i32 s20, s10, s80
	s_mul_i32 s20, s20, s11
	s_branch .LBB0_1104

.LBB0_1173:
	v_readlane_b32 s0, v238, 13
	s_add_i32 s38, s0, 9
	v_readlane_b32 s0, v245, 5
	v_readlane_b32 s1, v245, 6
	s_cmp_ge_i32 s38, s1
	s_cbranch_scc1 .LBB0_1227
	s_waitcnt vmcnt(0)
	s_waitcnt vmcnt(0) lgkmcnt(0)
	s_barrier
	s_mov_b64 s[0:1], exec
	v_readlane_b32 s10, v245, 3
	v_readlane_b32 s11, v245, 4
	s_and_b64 s[10:11], s[0:1], s[10:11]
	s_mov_b64 exec, s[10:11]
	s_cbranch_execz .LBB0_1226
	v_readlane_b32 s10, v239, 5
	s_waitcnt vmcnt(0) expcnt(0) lgkmcnt(0)
	buffer_inv sc1
	s_nop 0
	v_mov_b32_e32 v2, s10
	ds_read_b32 v4, v2
	v_readlane_b32 s10, v239, 6
	s_waitcnt lgkmcnt(0)
	v_cmp_ne_u32_e32 vcc, 0, v4
	v_mov_b32_e32 v2, s10
	ds_read_b32 v2, v2
	s_cbranch_vccnz .LBB0_1190
	v_readlane_b32 s14, v245, 0
	v_readlane_b32 s15, v245, 1
	s_load_dwordx2 s[10:11], s[14:15], 0x4
	s_mov_b32 s21, 1
	s_waitcnt lgkmcnt(0)
	s_mul_i32 s20, s10, s80
	s_mul_i32 s20, s20, s11
	s_branch .LBB0_1178

.LBB0_1353:
	v_readlane_b32 s0, v238, 13
	s_add_i32 s38, s0, 10
	v_readlane_b32 s0, v245, 5
	v_readlane_b32 s1, v245, 6
	s_cmp_ge_i32 s38, s1
	s_cbranch_scc1 .LBB0_1408
	s_waitcnt vmcnt(0)
	s_waitcnt vmcnt(0) lgkmcnt(0)
	s_barrier
	s_mov_b64 s[0:1], exec
	v_readlane_b32 s10, v245, 3
	v_readlane_b32 s11, v245, 4
	s_and_b64 s[10:11], s[0:1], s[10:11]
	s_mov_b64 exec, s[10:11]
	s_cbranch_execz .LBB0_1407
	v_readlane_b32 s10, v239, 5
	s_waitcnt vmcnt(0) expcnt(0) lgkmcnt(0)
	buffer_inv sc1
	s_nop 0
	v_mov_b32_e32 v2, s10
	ds_read_b32 v4, v2
	v_readlane_b32 s10, v239, 6
	s_waitcnt lgkmcnt(0)
	v_cmp_ne_u32_e32 vcc, 0, v4
	v_mov_b32_e32 v2, s10
	ds_read_b32 v2, v2
	s_cbranch_vccnz .LBB0_1370
	v_readlane_b32 s14, v245, 0
	v_readlane_b32 s15, v245, 1
	s_load_dwordx2 s[10:11], s[14:15], 0x4
	s_mov_b32 s21, 1
	s_waitcnt lgkmcnt(0)
	s_mul_i32 s20, s10, s80
	s_mul_i32 s20, s20, s11
	s_branch .LBB0_1358

.LBB0_1430:
	v_readlane_b32 s10, v239, 5
	s_waitcnt vmcnt(0) expcnt(0) lgkmcnt(0)
	buffer_inv sc1
	s_nop 0
	v_mov_b32_e32 v2, s10
	ds_read_b32 v4, v2
	v_readlane_b32 s10, v239, 6
	s_waitcnt lgkmcnt(0)
	v_cmp_ne_u32_e32 vcc, 0, v4
	v_mov_b32_e32 v2, s10
	ds_read_b32 v2, v2
	s_cbranch_vccnz .LBB0_1445
	v_readlane_b32 s14, v245, 0
	v_readlane_b32 s15, v245, 1
	s_load_dwordx2 s[10:11], s[14:15], 0x4
	s_mov_b32 s21, 1
	s_waitcnt lgkmcnt(0)
	s_mul_i32 s20, s10, s80
	s_mul_i32 s20, s20, s11
	s_branch .LBB0_1433

.LBB0_1478:
	s_or_b64 exec, exec, s[10:11]
	s_mov_b64 s[10:11], exec
	v_mbcnt_lo_u32_b32 v2, s10, 0
	v_mbcnt_hi_u32_b32 v2, s11, v2
	v_cmp_eq_u32_e32 vcc, 0, v2
	s_waitcnt vmcnt(0)
	s_and_saveexec_b64 s[14:15], vcc
	s_cbranch_execnz .LBB0_1479
	s_getpc_b64 s[98:99]
